# GEMM1 tile order: column-tile index permuted so the expensive-epilogue tiles (transposed outputs, new_v copies) are split evenly across XCDs
# baseline (speedup 1.0000x reference)
.LBB0_196:
	s_or_b64 exec, exec, s[2:3]
	s_add_u32 s8, s14, 0x13200000
	s_addc_u32 s9, s15, 0
	s_cmpk_lt_i32 s62, 0x180
	s_cselect_b64 s[0:1], -1, 0
	v_writelane_b32 v253, s0, 33
	v_mbcnt_hi_u32_b32 v228, -1, v10
	v_and_b32_e32 v2, 64, v228
	v_writelane_b32 v253, s1, 34
	s_add_u32 s0, s14, 0xa000000
	v_writelane_b32 v253, s0, 35
	s_addc_u32 s0, s15, 0
	s_cmp_eq_u32 s42, 15
	v_writelane_b32 v253, s0, 36
	s_cselect_b64 s[0:1], -1, 0
	v_writelane_b32 v253, s0, 37
	s_cmp_eq_u32 s42, 14
	s_waitcnt lgkmcnt(0)
	v_writelane_b32 v253, s1, 38
	s_cselect_b64 s[0:1], -1, 0
	v_writelane_b32 v253, s0, 39
	s_cmp_eq_u32 s42, 13
	s_barrier
	v_writelane_b32 v253, s1, 40
	s_cselect_b64 s[0:1], -1, 0
	v_writelane_b32 v253, s0, 41
	s_cmp_eq_u32 s42, 12
	s_nop 0
	v_writelane_b32 v253, s1, 42
	s_cselect_b64 s[0:1], -1, 0
	v_writelane_b32 v253, s0, 43
	s_cmp_eq_u32 s42, 11
	s_mov_b32 s83, 0x20000
	v_writelane_b32 v253, s1, 44
	s_cselect_b64 s[0:1], -1, 0
	v_writelane_b32 v253, s0, 45
	s_cmp_eq_u32 s42, 10
	s_mov_b32 s82, 0x3000000
	v_writelane_b32 v253, s1, 46
	s_cselect_b64 s[0:1], -1, 0
	v_writelane_b32 v253, s0, 47
	s_cmp_eq_u32 s42, 9
	v_mov_b32_e32 v0, 0
	v_writelane_b32 v253, s1, 48
	s_cselect_b64 s[0:1], -1, 0
	v_writelane_b32 v253, s0, 49
	s_cmp_eq_u32 s42, 8
	v_mov_b32_e32 v221, 0x358637bd
	v_writelane_b32 v253, s1, 50
	s_cselect_b64 s[0:1], -1, 0
	v_writelane_b32 v253, s0, 51
	s_cmp_eq_u32 s42, 7
	v_mov_b32_e32 v222, 0xc0447cbd
	v_writelane_b32 v253, s1, 52
	s_cselect_b64 s[0:1], -1, 0
	v_writelane_b32 v253, s0, 53
	s_cmp_eq_u32 s42, 6
	v_mov_b32_e32 v223, 1
	v_writelane_b32 v253, s1, 54
	s_cselect_b64 s[0:1], -1, 0
	v_writelane_b32 v253, s0, 55
	s_cmp_eq_u32 s42, 5
	v_mov_b32_e32 v198, 1.0
	v_writelane_b32 v253, s1, 56
	s_cselect_b64 s[0:1], -1, 0
	v_writelane_b32 v253, s0, 57
	s_cmp_eq_u32 s42, 4
	v_mov_b32_e32 v224, 0x3000
	v_writelane_b32 v253, s1, 58
	s_cselect_b64 s[0:1], -1, 0
	v_writelane_b32 v253, s0, 59
	s_cmp_eq_u32 s42, 3
	v_mov_b32_e32 v225, 0x1000
	v_writelane_b32 v253, s1, 60
	s_cselect_b64 s[0:1], -1, 0
	v_writelane_b32 v253, s0, 61
	s_cmp_eq_u32 s42, 2
	v_mov_b32_e32 v226, 0x2000
	v_writelane_b32 v253, s1, 62
	s_cselect_b64 s[0:1], -1, 0
	v_writelane_b32 v253, s0, 63
	s_cmp_eq_u32 s42, 1
	v_mov_b32_e32 v227, 0x4000
	v_writelane_b32 v254, s1, 0
	s_cselect_b64 s[0:1], -1, 0
	v_writelane_b32 v254, s0, 1
	s_cmp_eq_u32 s42, 0
	v_add_u32_e32 v229, 64, v2
	v_writelane_b32 v254, s1, 2
	s_cselect_b64 s[0:1], -1, 0
	s_add_u32 s94, s14, 0x16200000
	s_addc_u32 s95, s15, 0
	s_add_u32 s84, s12, 0xa000000
	s_addc_u32 s85, s13, 0
	v_writelane_b32 v254, s0, 3
	s_cmpk_lt_i32 s62, 0x9c0
	v_xor_b32_e32 v230, 1, v228
	v_writelane_b32 v254, s1, 4
	s_cselect_b64 s[0:1], -1, 0
	v_writelane_b32 v254, s0, 5
	s_ashr_i32 s57, s62, 31
	v_xor_b32_e32 v231, 2, v228
	v_writelane_b32 v254, s1, 6
	s_lshr_b32 s0, s57, 29
	s_add_i32 s0, s62, s0
	s_ashr_i32 s2, s0, 3
	s_and_b32 s0, s0, -8
	s_sub_i32 s3, s62, s0
	s_ashr_i32 s0, s60, 31
	s_add_u32 s6, s14, 0x2d600000
	s_addc_u32 s7, s15, 0
	v_writelane_b32 v254, s0, 7
	s_add_u32 s0, s14, 0x8c00000
	v_writelane_b32 v254, s0, 8
	s_addc_u32 s0, s15, 0
	v_writelane_b32 v254, s0, 9
	s_add_u32 s0, s14, 0x29a00000
	v_writelane_b32 v254, s0, 10
	s_addc_u32 s0, s15, 0
	v_writelane_b32 v254, s0, 11
	s_add_u32 s0, s12, 0x6000000
	v_writelane_b32 v254, s0, 12
	s_addc_u32 s0, s13, 0
	v_writelane_b32 v254, s0, 13
	s_add_u32 s0, s14, 0x2a600000
	s_addc_u32 s1, s15, 0
	v_writelane_b32 v254, s0, 14
	v_xor_b32_e32 v232, 4, v228
	v_xor_b32_e32 v233, 8, v228
	v_writelane_b32 v254, s1, 15
	s_add_u32 s0, s14, 0xb400000
	s_addc_u32 s1, s15, 0
	v_writelane_b32 v254, s0, 16
	v_xor_b32_e32 v234, 16, v228
	v_xor_b32_e32 v235, 32, v228
	v_writelane_b32 v254, s1, 17
	s_add_u32 s0, s14, 0xb800000
	s_addc_u32 s1, s15, 0
	s_add_u32 s78, s14, 0x2c600000
	v_writelane_b32 v254, s0, 18
	s_addc_u32 s79, s15, 0
	v_mov_b32_e32 v236, 0xf0
	v_writelane_b32 v254, s1, 19
	s_add_u32 s0, s14, 0x8d00000
	v_writelane_b32 v254, s0, 20
	s_addc_u32 s0, s15, 0
	v_writelane_b32 v254, s0, 21
	s_add_u32 s0, s14, 0x2a200000
	v_writelane_b32 v254, s0, 22
	s_addc_u32 s0, s15, 0
	v_writelane_b32 v254, s0, 23
	s_add_u32 s0, s14, 0x8000
	v_writelane_b32 v254, s0, 24
	s_addc_u32 s0, s15, 0
	v_writelane_b32 v254, s0, 25
	s_add_u32 s0, s12, 0x4000000
	v_writelane_b32 v254, s0, 26
	s_addc_u32 s0, s13, 0
	v_writelane_b32 v254, s0, 27
	s_lshl_b32 s0, s62, 5
	s_and_b32 s0, s0, 0xe0
	s_ashr_i32 s1, s62, 3
	s_add_i32 s0, s0, s1
	s_cmpk_eq_i32 s60, 0x100
	s_cselect_b32 s4, s0, s62
	s_cmpk_lt_i32 s4, 0x300
	s_cselect_b64 s[0:1], -1, 0
	s_and_b32 s10, s4, 7
	s_cmpk_gt_i32 s4, 0x17f
	v_writelane_b32 v254, s0, 28
	s_cselect_b64 s[16:17], -1, 0
	v_cndmask_b32_e64 v1, 0, 1, s[16:17]
	v_writelane_b32 v254, s1, 29
	s_and_b64 s[0:1], s[16:17], exec
	s_cselect_b32 s0, 0xfffffe80, 0
	v_writelane_b32 v254, s4, 30
	s_add_i32 s0, s0, s4
	s_ashr_i32 s18, s0, 3
	v_writelane_b32 v254, s16, 31
	s_and_b64 s[0:1], s[16:17], exec
	s_cselect_b32 s4, s9, s7
	v_writelane_b32 v254, s17, 32
	v_writelane_b32 v254, s6, 33
	s_cselect_b32 s5, s8, s6
	s_ashr_i32 s19, s18, 31
	s_lshl_b64 s[0:1], s[18:19], 20
	v_writelane_b32 v254, s7, 34
	s_add_u32 s16, s5, s0
	s_mov_b32 s0, s18
	s_addc_u32 s17, s4, s1
	v_writelane_b32 v254, s0, 35
	s_lshl_b32 s4, s10, 20
	v_mov_b64_e32 v[200:201], 0x9c0
	v_writelane_b32 v254, s1, 36
	s_lshl_b32 s0, s18, 6
	v_writelane_b32 v254, s10, 37
	s_ashr_i32 s1, s0, 31
	v_writelane_b32 v254, s4, 38
	s_add_u32 s4, s16, 0x80000
	v_writelane_b32 v254, s16, 39
	s_addc_u32 s5, s17, 0
	v_mov_b64_e32 v[202:203], 0x9bf
	v_writelane_b32 v254, s17, 40
	v_writelane_b32 v254, s4, 41
	v_mov_b32_e32 v237, 0xcf
	s_movk_i32 s46, 0x1ff
	v_writelane_b32 v254, s5, 42
	s_add_u32 s4, s14, 0x16203800
	s_addc_u32 s5, s15, 0
	v_writelane_b32 v254, s4, 43
	s_and_b32 s81, s9, 0xffff
	s_cmp_lt_i32 s3, 0
	v_writelane_b32 v254, s5, 44
	s_movk_i32 s4, 0x139
	s_cselect_b32 s4, s4, 0x138
	s_mul_i32 s3, s3, s4
	s_add_i32 s3, s3, s2
	s_mul_hi_i32 s2, s3, 0x4ec4ec4f
	s_lshr_b32 s4, s2, 31
	s_ashr_i32 s2, s2, 6
	s_add_i32 s2, s2, s4
	s_mul_i32 s4, s2, 0xd0
	s_sub_i32 s3, s3, s4
	s_bfe_u32 s4, s3, 0x2001d
	s_add_i32 s4, s3, s4
	s_and_b32 s5, s4, 0xfffc
	s_sub_i32 s3, s3, s5
	s_lshl_b32 s2, s2, 2
	s_sext_i32_i16 s4, s4
	s_sext_i32_i16 s3, s3
	s_add_i32 s10, s2, s3
	s_ashr_i32 s2, s4, 2
	s_lshl_b32 s100, s2, 1
	s_sub_u32 s101, s100, 51
	s_cmp_lt_u32 s2, 26
	s_cselect_b32 s2, s100, s101
	s_mov_b32 s100, s2
	v_writelane_b32 v254, s2, 45
	s_mov_b32 s2, s100
	s_bfe_i64 s[2:3], s[2:3], 0x100000
	s_lshl_b64 s[2:3], s[2:3], 20
	v_writelane_b32 v254, s2, 46
	s_ashr_i32 s11, s10, 31
	s_movk_i32 s18, 0x7fff
	v_writelane_b32 v254, s3, 47
	s_mov_b32 s2, s10
	v_writelane_b32 v254, s2, 48
	s_movk_i32 s52, 0x420
	s_movk_i32 s47, 0x2000
	v_writelane_b32 v254, s3, 49
	s_lshl_b64 s[2:3], s[10:11], 20
	s_add_u32 s4, s8, s2
	s_mul_i32 s2, s61, s60
	s_mul_i32 s2, s2, s33
	v_writelane_b32 v254, s2, 50
	s_addc_u32 s5, s9, s3
	v_writelane_b32 v254, s8, 51
	s_add_u32 s2, s4, 0x80000
	s_mov_b32 s80, s8
	v_writelane_b32 v254, s9, 52
	v_writelane_b32 v254, s4, 53
	s_addc_u32 s3, s5, 0
	s_lshl_b64 s[0:1], s[0:1], 2
	v_writelane_b32 v254, s5, 54
	v_writelane_b32 v254, s2, 55
	s_ashr_i32 s59, s58, 31
	s_add_i32 s56, 0, 0x23fc0
	v_writelane_b32 v254, s3, 56
	v_writelane_b32 v254, s0, 57
	s_movk_i32 s21, 0x90
	s_movk_i32 s53, 0xdff
	v_writelane_b32 v254, s1, 58
	v_readfirstlane_b32 s0, v1
	s_movk_i32 s20, 0x6800
	s_mov_b32 s33, 0x1000706
	v_writelane_b32 v254, s0, 59
	s_add_i32 s0, 0, 0x4000
	v_writelane_b32 v254, s0, 60
	s_add_i32 s0, 0, 0x23fd0
	v_writelane_b32 v254, s0, 61
	s_add_i32 s0, 0, 0x23fd4
	v_writelane_b32 v254, s0, 62
	s_add_i32 s0, 0, 0x12800
	v_writelane_b32 v254, s0, 63
	s_add_i32 s0, 0, 0x10100
	v_writelane_b32 v252, s0, 0
	s_add_i32 s0, 0, 0x1ad00
	v_writelane_b32 v252, s0, 1
	s_add_i32 s0, 0, 0x12500
	v_writelane_b32 v252, s0, 2
	s_add_i32 s0, 0, 0x16900
	v_writelane_b32 v252, s0, 3
	s_lshl_b64 s[0:1], s[58:59], 13
	v_writelane_b32 v252, s0, 4
	s_mov_b32 s97, 0
	s_mov_b32 s35, 0
	v_writelane_b32 v252, s1, 5
	s_mov_b64 s[0:1], -1
	v_writelane_b32 v252, s0, 6
	s_mov_b64 s[26:27], 0x1000
	s_mov_b64 s[30:31], 0x80
	v_writelane_b32 v252, s1, 7
	v_writelane_b32 v252, s62, 8
	v_writelane_b32 v252, s58, 9
	s_nop 1
	v_writelane_b32 v252, s59, 10
	v_writelane_b32 v252, s57, 11
	v_writelane_b32 v252, s56, 12
	v_writelane_b32 v252, s84, 13
	s_nop 1
	v_writelane_b32 v252, s85, 14
	s_branch .LBB0_200

.LBB0_309:
	s_add_i32 s49, s49, 1
	v_readlane_b32 s16, v254, 7
	s_mul_i32 s16, s49, s16
	s_mul_hi_u32 s17, s49, s60
	s_add_i32 s17, s17, s16
	s_mul_i32 s16, s49, s60
	s_add_u32 s16, s16, s62
	s_addc_u32 s17, s17, s57
	v_cmp_gt_i64_e32 vcc, s[16:17], v[202:203]
	v_cmp_lt_i64_e64 s[38:39], s[16:17], v[200:201]
	s_cbranch_vccnz .LBB0_311
	s_ashr_i32 s17, s16, 31
	s_lshr_b32 s17, s17, 29
	s_add_i32 s17, s16, s17
	s_ashr_i32 s28, s17, 3
	s_and_b32 s17, s17, -8
	s_sub_i32 s16, s16, s17
	s_cmp_lt_i32 s16, 0
	s_movk_i32 s17, 0x139
	s_cselect_b32 s17, s17, 0x138
	s_mul_i32 s16, s16, s17
	s_add_i32 s16, s16, s28
	s_mul_hi_i32 s17, s16, 0x4ec4ec4f
	s_lshr_b32 s28, s17, 31
	s_ashr_i32 s17, s17, 6
	s_add_i32 s17, s17, s28
	s_lshl_b32 s29, s17, 2
	s_sub_i32 s28, 48, s29
	s_min_i32 s36, s28, 4
	s_abs_i32 s28, s36
	v_cvt_f32_u32_e32 v2, s28
	s_sub_i32 s40, 0, s28
	s_mulk_i32 s17, 0xd0
	s_sub_i32 s16, s16, s17
	v_rcp_iflag_f32_e32 v2, v2
	s_abs_i32 s17, s16
	s_xor_b32 s37, s16, s36
	s_ashr_i32 s37, s37, 31
	v_mul_f32_e32 v2, 0x4f7ffffe, v2
	v_cvt_u32_f32_e32 v2, v2
	s_nop 0
	v_readfirstlane_b32 s41, v2
	s_mul_i32 s40, s40, s41
	s_mul_hi_u32 s40, s41, s40
	s_add_i32 s41, s41, s40
	s_mul_hi_u32 s40, s17, s41
	s_mul_i32 s41, s40, s28
	s_sub_i32 s17, s17, s41
	s_add_i32 s42, s40, 1
	s_sub_i32 s41, s17, s28
	s_cmp_ge_u32 s17, s28
	s_cselect_b32 s40, s42, s40
	s_cselect_b32 s17, s41, s17
	s_add_i32 s41, s40, 1
	s_cmp_ge_u32 s17, s28
	s_cselect_b32 s17, s41, s40
	s_xor_b32 s17, s17, s37
	s_sub_i32 s28, s17, s37
	s_mul_i32 s17, s28, s36
	s_sub_i32 s16, s16, s17
	s_add_i32 s36, s29, s16
	s_lshl_b32 s16, s28, 1
	s_sub_u32 s17, s16, 51
	s_cmp_lt_u32 s28, 26
	s_cselect_b32 s28, s16, s17
